# v013 plus one static s_setprio 1 for waves 4-7 over each attention kv loop
# speedup vs baseline: 1.0037x; 1.0037x over previous
.Lh1_first:
	s_cmp_lt_u32 s96, 4
	s_cbranch_scc1 .Lprio_skip
	s_setprio 1

.LBB0_420:
	s_setprio 0
	s_xor_b64 s[10:11], s[74:75], -1
	s_lshl_b32 s6, s6, 6
	s_cmp_le_i32 s6, s5
	s_cselect_b64 s[74:75], -1, 0
	s_and_b64 vcc, exec, s[74:75]
	s_cbranch_vccz .LBB0_422
	ds_read_b128 v[2:5], v196 offset:57344
	ds_read_b128 v[6:9], v196 offset:57472
	s_waitcnt lgkmcnt(1)
	v_mfma_f32_32x32x16_bf16 v[112:127], v[2:5], v[156:159], 0
	ds_read_b128 v[2:5], v207 offset:12288
	ds_read_b128 v[10:13], v207 offset:12416
	s_waitcnt lgkmcnt(1)
	v_mfma_f32_32x32x16_bf16 v[96:111], v[2:5], v[156:159], 0
	ds_read_b128 v[2:5], v197 offset:57344
	ds_read_b128 v[18:21], v196 offset:57600
	s_waitcnt lgkmcnt(1)
	v_mfma_f32_32x32x16_bf16 v[112:127], v[2:5], v[152:155], v[112:127]
	ds_read_b128 v[2:5], v205 offset:12288
	ds_read_b128 v[22:25], v207 offset:12544
	s_waitcnt lgkmcnt(1)
	v_mfma_f32_32x32x16_bf16 v[96:111], v[2:5], v[152:155], v[96:111]
	ds_read_b128 v[2:5], v199 offset:57344
	ds_read_b128 v[26:29], v199 offset:57472
	s_waitcnt lgkmcnt(1)
	v_mfma_f32_32x32x16_bf16 v[112:127], v[2:5], v[148:151], v[112:127]
	ds_read_b128 v[2:5], v206 offset:12288
	ds_read_b128 v[152:155], v206 offset:12416
	s_waitcnt lgkmcnt(1)
	v_mfma_f32_32x32x16_bf16 v[96:111], v[2:5], v[148:151], v[96:111]
	ds_read_b128 v[2:5], v198 offset:57344
	ds_read_b128 v[148:151], v199 offset:57600
	s_waitcnt lgkmcnt(1)
	v_mfma_f32_32x32x16_bf16 v[112:127], v[2:5], v[144:147], v[112:127]
	ds_read_b128 v[2:5], v204 offset:12288
	ds_read_b128 v[156:159], v206 offset:12544
	s_waitcnt lgkmcnt(1)
	v_mfma_f32_32x32x16_bf16 v[96:111], v[2:5], v[144:147], v[96:111]
	v_mfma_f32_32x32x16_bf16 v[112:127], v[6:9], v[140:143], v[112:127]
	ds_read_b128 v[2:5], v197 offset:57472
	ds_read_b128 v[6:9], v197 offset:57600
	v_mfma_f32_32x32x16_bf16 v[96:111], v[10:13], v[140:143], v[96:111]
	s_waitcnt lgkmcnt(1)
	v_mfma_f32_32x32x16_bf16 v[112:127], v[2:5], v[136:139], v[112:127]
	ds_read_b128 v[2:5], v205 offset:12416
	ds_read_b128 v[10:13], v205 offset:12544
	s_waitcnt lgkmcnt(1)
	v_mfma_f32_32x32x16_bf16 v[96:111], v[2:5], v[136:139], v[96:111]
	v_mfma_f32_32x32x16_bf16 v[112:127], v[26:29], v[132:135], v[112:127]
	ds_read_b128 v[2:5], v198 offset:57472
	ds_read_b128 v[26:29], v198 offset:57600
	v_mfma_f32_32x32x16_bf16 v[96:111], v[152:155], v[132:135], v[96:111]
	s_waitcnt lgkmcnt(1)
	v_mfma_f32_32x32x16_bf16 v[112:127], v[2:5], v[128:131], v[112:127]
	ds_read_b128 v[2:5], v204 offset:12416
	ds_read_b128 v[132:135], v204 offset:12544
	s_waitcnt lgkmcnt(1)
	v_mfma_f32_32x32x16_bf16 v[96:111], v[2:5], v[128:131], v[96:111]
	ds_read_b128 v[2:5], v195
	ds_read_b128 v[128:131], v195 offset:1024
	s_waitcnt lgkmcnt(1)
	v_mfma_f32_32x32x16_bf16 v[112:127], v[18:21], v[2:5], v[112:127]
	v_mfma_f32_32x32x16_bf16 v[96:111], v[22:25], v[2:5], v[96:111]
	s_waitcnt lgkmcnt(0)
	v_mfma_f32_32x32x16_bf16 v[112:127], v[6:9], v[128:131], v[112:127]
	ds_read_b128 v[2:5], v195 offset:2048
	ds_read_b128 v[6:9], v195 offset:3072
	v_mfma_f32_32x32x16_bf16 v[96:111], v[10:13], v[128:131], v[96:111]
	s_waitcnt lgkmcnt(1)
	v_mfma_f32_32x32x16_bf16 v[112:127], v[148:151], v[2:5], v[112:127]
	v_mfma_f32_32x32x16_bf16 v[96:111], v[156:159], v[2:5], v[96:111]
	s_waitcnt lgkmcnt(0)
	v_mfma_f32_32x32x16_bf16 v[112:127], v[26:29], v[6:9], v[112:127]
	v_mfma_f32_32x32x16_bf16 v[96:111], v[132:135], v[6:9], v[96:111]
	s_branch .LBB0_423
